# attn1: softmax reference folded into the S accumulate chain (extra ones x bf16(-mref) MFMA, mref kept bf16-exact), removes 64 v_sub per tile; K1 frags reuse K0 registers
# speedup vs baseline: 1.0444x; 1.0107x over previous
; template <int DQ, bool BIAS, bool TAIL>
; __device__ __forceinline__ void attn_item(const AttnItem& A, LAS unsigned char* lds, int wave_s_) {
;     ...
;                 s[0] = MFMA32(kf[0], qf[0][0], zero16v); s[1] = MFMA32(kf[0], qf[1][0], zero16v);
; #pragma unroll
;                 for (int kk = 1; kk < NKK; ++kk) { s[0] = MFMA32(kf[kk], qf[0][kk], s[0]); s[1] = MFMA32(kf[kk], qf[1][kk], s[1]); }
;                 s16x4 vlo[2][2], vhi[2][2];
; #pragma unroll
;                 for (int st = 0; st < 2; ++st)
; #pragma unroll
;                     for (int d = 0; d < 2; ++d) { const LAS unsigned char* vp = vb + ((32 * kbk + 16 * st) * VROW + 32 * d) * 2; vlo[st][d] = vtr(vp); vhi[st][d] = vtr(vp + 8 * VROW * 2); }
;                 __builtin_amdgcn_sched_barrier(0);
;                 float mx[2];
; #pragma unroll
;                 for (int qb = 0; qb < 2; ++qb) {
;                     if (BIAS || TAIL) {
;                         const int qk = A.q_kidx0 + 64 * w + 32 * qb + r32;
; #pragma unroll
;                         for (int i = 0; i < 16; ++i) { const int kidx = 64 * t + 32 * kbk + crow(i, hi);
;                             float v = s[qb][i]; if (BIAS) v += lut[kidx - qk + LUT0]; if (TAIL && kidx >= A.nkeys) v = -1.0e30f; s[qb][i] = v; }
;                     }
;                     const float t0 = max3f(s[qb][0], s[qb][1], s[qb][2]), t1 = max3f(s[qb][3], s[qb][4], s[qb][5]), t2 = max3f(s[qb][6], s[qb][7], s[qb][8]),
;                                 t3 = max3f(s[qb][9], s[qb][10], s[qb][11]), t4 = max3f(s[qb][12], s[qb][13], s[qb][14]);
;                     const float m = max3f(max3f(t0, t1, t2), max3f(t3, t4, s[qb][15]), t0);
;                     mx[qb] = swapmax(m, hi) - mref[qb];
;                 }
;                 const bool need0 = first || mx[0] > RESCALE_THR, need1 = first || mx[1] > RESCALE_THR;
;                 if (__builtin_amdgcn_ballot_w64(need0 || need1) != 0ull) {
; #pragma unroll
;                     for (int qb = 0; qb < 2; ++qb) {
;                         const float delta = (qb == 0 ? need0 : need1) ? mx[qb] : 0.f, alpha = __builtin_amdgcn_exp2f(-delta);
; #pragma unroll
;                         for (int i = 0; i < 16; ++i) { o[0][qb][i] *= alpha; o[1][qb][i] *= alpha; }
;                         lrun[qb] *= alpha; mref[qb] += delta;
;                     }
;                     first = false;
;                 }
.Lp7_body:
	s_mul_i32 s8, s21, 0x2400
	v_add_u32_e32 v229, s8, v227
	v_mfma_f32_32x32x16_bf16 v[80:95], v[230:233], v[238:241], 0
	s_waitcnt lgkmcnt(5)
	v_mfma_f32_32x32x16_bf16 v[80:95], v[176:179], v[96:99], v[80:95]
	ds_read_b64_tr_b16 v[192:193], v229 offset:26624
	ds_read_b64_tr_b16 v[194:195], v229 offset:27776
	ds_read_b64_tr_b16 v[188:189], v229 offset:26688
	ds_read_b64_tr_b16 v[190:191], v229 offset:27840
	ds_read_b64_tr_b16 v[184:185], v229 offset:28928
	ds_read_b64_tr_b16 v[186:187], v229 offset:30080
	ds_read_b64_tr_b16 v[180:181], v229 offset:28992
	ds_read_b64_tr_b16 v[182:183], v229 offset:30144
	s_waitcnt lgkmcnt(12)
	v_mfma_f32_32x32x16_bf16 v[80:95], v[172:175], v[100:103], v[80:95]
	s_waitcnt lgkmcnt(11)
	v_mfma_f32_32x32x16_bf16 v[80:95], v[168:171], v[104:107], v[80:95]
	s_waitcnt lgkmcnt(10)
	v_mfma_f32_32x32x16_bf16 v[80:95], v[164:167], v[108:111], v[80:95]
	s_waitcnt lgkmcnt(9)
	v_mfma_f32_32x32x16_bf16 v[80:95], v[160:163], v[112:115], v[80:95]
	s_waitcnt lgkmcnt(8)
	v_mfma_f32_32x32x16_bf16 v[80:95], v[156:159], v[116:119], v[80:95]
	v_mfma_f32_32x32x16_bf16 v[64:79], v[230:233], v[246:249], 0
	v_mfma_f32_32x32x16_bf16 v[64:79], v[176:179], v[120:123], v[64:79]
	ds_read_b128 v[176:179], v196 offset:6656
	v_mfma_f32_32x32x16_bf16 v[64:79], v[172:175], v[124:127], v[64:79]
	ds_read_b128 v[172:175], v196 offset:6688
	s_nop 7
	v_exp_f32_e32 v80, v80
	v_exp_f32_e32 v81, v81
	v_exp_f32_e32 v82, v82
	v_exp_f32_e32 v83, v83
	v_exp_f32_e32 v84, v84
	v_exp_f32_e32 v85, v85
	v_mfma_f32_32x32x16_bf16 v[64:79], v[168:171], v[128:131], v[64:79]
	ds_read_b128 v[168:171], v196 offset:6720
	v_exp_f32_e32 v86, v86
	v_exp_f32_e32 v87, v87
	v_add_f32_e32 v198, v80, v84
	v_add_f32_e32 v199, v81, v85
	v_add_f32_e32 v204, v82, v86
	v_add_f32_e32 v205, v83, v87
	v_exp_f32_e32 v88, v88
	v_exp_f32_e32 v89, v89
	v_mfma_f32_32x32x16_bf16 v[64:79], v[164:167], v[132:135], v[64:79]
	ds_read_b128 v[164:167], v196 offset:6752
	v_exp_f32_e32 v90, v90
	v_exp_f32_e32 v91, v91
	v_add_f32_e32 v198, v198, v88
	v_add_f32_e32 v199, v199, v89
	v_add_f32_e32 v204, v204, v90
	v_add_f32_e32 v205, v205, v91
	v_exp_f32_e32 v92, v92
	v_exp_f32_e32 v93, v93
	v_mfma_f32_32x32x16_bf16 v[64:79], v[160:163], v[140:143], v[64:79]
	ds_read_b128 v[160:163], v196 offset:6784
	v_exp_f32_e32 v94, v94
	v_exp_f32_e32 v95, v95
	v_add_f32_e32 v198, v198, v92
	v_add_f32_e32 v199, v199, v93
	v_add_f32_e32 v204, v204, v94
	v_add_f32_e32 v205, v205, v95
	v_mfma_f32_32x32x16_bf16 v[64:79], v[156:159], v[136:139], v[64:79]
	ds_read_b128 v[156:159], v196 offset:6816
	v_add_f32_e32 v198, v198, v199
	v_add_f32_e32 v204, v204, v205
	v_add_f32_e32 v198, v198, v204
	v_cmp_lt_f32_e32 vcc, 0x44800000, v198
	s_or_b32 s8, vcc_lo, vcc_hi
	s_mov_b32 s9, s8
	s_cbranch_scc1 .Lp7_rare_00
.Lp7_back_00:
	v_cvt_pk_bf16_f32 v80, v80, v81
	v_cvt_pk_bf16_f32 v81, v82, v83
	v_cvt_pk_bf16_f32 v82, v84, v85
	v_cvt_pk_bf16_f32 v83, v86, v87
	v_add_f32_e32 v212, v212, v198
	v_cvt_pk_bf16_f32 v84, v88, v89
	v_cvt_pk_bf16_f32 v85, v90, v91
	v_cvt_pk_bf16_f32 v86, v92, v93
	v_cvt_pk_bf16_f32 v87, v94, v95
	v_exp_f32_e32 v64, v64
	v_exp_f32_e32 v65, v65
	s_waitcnt lgkmcnt(12)
	v_mfma_f32_32x32x16_bf16 v[48:63], v[192:195], v[80:83], v[48:63]
	v_exp_f32_e32 v66, v66
	v_exp_f32_e32 v67, v67
	s_waitcnt lgkmcnt(10)
	v_mfma_f32_32x32x16_bf16 v[32:47], v[188:191], v[80:83], v[32:47]
	v_exp_f32_e32 v68, v68
	v_exp_f32_e32 v69, v69
	s_waitcnt lgkmcnt(8)
	v_mfma_f32_32x32x16_bf16 v[48:63], v[184:187], v[84:87], v[48:63]
	v_exp_f32_e32 v70, v70
	v_exp_f32_e32 v71, v71
	s_waitcnt lgkmcnt(6)
	v_mfma_f32_32x32x16_bf16 v[32:47], v[180:183], v[84:87], v[32:47]
	v_add_f32_e32 v198, v64, v68
	v_add_f32_e32 v199, v65, v69
	v_mfma_f32_32x32x16_bf16 v[80:95], v[230:233], v[238:241], 0
	v_add_f32_e32 v204, v66, v70
	v_add_f32_e32 v205, v67, v71
	v_exp_f32_e32 v72, v72
	s_waitcnt lgkmcnt(5)
	v_mfma_f32_32x32x16_bf16 v[80:95], v[176:179], v[96:99], v[80:95]
	v_exp_f32_e32 v73, v73
	v_exp_f32_e32 v74, v74
	v_exp_f32_e32 v75, v75
	s_waitcnt lgkmcnt(4)
	v_mfma_f32_32x32x16_bf16 v[80:95], v[172:175], v[100:103], v[80:95]
	v_add_f32_e32 v198, v198, v72
	v_add_f32_e32 v199, v199, v73
	v_add_f32_e32 v204, v204, v74
	s_waitcnt lgkmcnt(3)
	v_mfma_f32_32x32x16_bf16 v[80:95], v[168:171], v[104:107], v[80:95]
	v_add_f32_e32 v205, v205, v75
	v_exp_f32_e32 v76, v76
	v_exp_f32_e32 v77, v77
	s_waitcnt lgkmcnt(2)
	v_mfma_f32_32x32x16_bf16 v[80:95], v[164:167], v[108:111], v[80:95]
	v_exp_f32_e32 v78, v78
	v_exp_f32_e32 v79, v79
	v_add_f32_e32 v198, v198, v76
	s_waitcnt lgkmcnt(1)
	v_mfma_f32_32x32x16_bf16 v[80:95], v[160:163], v[112:115], v[80:95]
	v_add_f32_e32 v199, v199, v77
	v_add_f32_e32 v204, v204, v78
	v_add_f32_e32 v205, v205, v79
	s_waitcnt lgkmcnt(0)
	v_mfma_f32_32x32x16_bf16 v[80:95], v[156:159], v[116:119], v[80:95]
	v_add_f32_e32 v198, v198, v199
	v_add_f32_e32 v204, v204, v205
	v_add_f32_e32 v198, v198, v204
	v_cmp_lt_f32_e32 vcc, 0x44800000, v198
	s_or_b32 s8, vcc_lo, vcc_hi
	s_mov_b32 s9, s8
	s_cbranch_scc1 .Lp7_rare_01
; template <int DQ, bool BIAS, bool TAIL>
; __device__ __forceinline__ void attn_item(const AttnItem& A, LAS unsigned char* lds, int wave_s_) {
;     ...
;                 s[0] = MFMA32(kf[0], qf[0][0], zero16v); s[1] = MFMA32(kf[0], qf[1][0], zero16v);
; #pragma unroll
;                 for (int kk = 1; kk < NKK; ++kk) { s[0] = MFMA32(kf[kk], qf[0][kk], s[0]); s[1] = MFMA32(kf[kk], qf[1][kk], s[1]); }
;                 s16x4 vlo[2][2], vhi[2][2];
; #pragma unroll
;                 for (int st = 0; st < 2; ++st)
; #pragma unroll
;                     for (int d = 0; d < 2; ++d) { const LAS unsigned char* vp = vb + ((32 * kbk + 16 * st) * VROW + 32 * d) * 2; vlo[st][d] = vtr(vp); vhi[st][d] = vtr(vp + 8 * VROW * 2); }
;                 __builtin_amdgcn_sched_barrier(0);
;                 float mx[2];
; #pragma unroll
;                 for (int qb = 0; qb < 2; ++qb) {
;                     if (BIAS || TAIL) {
;                         const int qk = A.q_kidx0 + 64 * w + 32 * qb + r32;
; #pragma unroll
;                         for (int i = 0; i < 16; ++i) { const int kidx = 64 * t + 32 * kbk + crow(i, hi);
;                             float v = s[qb][i]; if (BIAS) v += lut[kidx - qk + LUT0]; if (TAIL && kidx >= A.nkeys) v = -1.0e30f; s[qb][i] = v; }
;                     }
;                     const float t0 = max3f(s[qb][0], s[qb][1], s[qb][2]), t1 = max3f(s[qb][3], s[qb][4], s[qb][5]), t2 = max3f(s[qb][6], s[qb][7], s[qb][8]),
;                                 t3 = max3f(s[qb][9], s[qb][10], s[qb][11]), t4 = max3f(s[qb][12], s[qb][13], s[qb][14]);
;                     const float m = max3f(max3f(t0, t1, t2), max3f(t3, t4, s[qb][15]), t0);
;                     mx[qb] = swapmax(m, hi) - mref[qb];
;                 }
;                 const bool need0 = first || mx[0] > RESCALE_THR, need1 = first || mx[1] > RESCALE_THR;
;                 if (__builtin_amdgcn_ballot_w64(need0 || need1) != 0ull) {
; #pragma unroll
;                     for (int qb = 0; qb < 2; ++qb) {
;                         const float delta = (qb == 0 ? need0 : need1) ? mx[qb] : 0.f, alpha = __builtin_amdgcn_exp2f(-delta);
; #pragma unroll
;                         for (int i = 0; i < 16; ++i) { o[0][qb][i] *= alpha; o[1][qb][i] *= alpha; }
;                         lrun[qb] *= alpha; mref[qb] += delta;
;                     }
;                     first = false;
;                 }
.Lp7_back_01:
	v_cvt_pk_bf16_f32 v64, v64, v65
	v_cvt_pk_bf16_f32 v65, v66, v67
	v_cvt_pk_bf16_f32 v66, v68, v69
	v_cvt_pk_bf16_f32 v67, v70, v71
	v_add_f32_e32 v213, v213, v198
	v_cvt_pk_bf16_f32 v68, v72, v73
	v_cvt_pk_bf16_f32 v69, v74, v75
	v_cvt_pk_bf16_f32 v70, v76, v77
	v_cvt_pk_bf16_f32 v71, v78, v79
	v_exp_f32_e32 v80, v80
	v_exp_f32_e32 v81, v81
	v_mfma_f32_32x32x16_bf16 v[16:31], v[192:195], v[64:67], v[16:31]
	v_exp_f32_e32 v82, v82
	v_exp_f32_e32 v83, v83
	v_mfma_f32_32x32x16_bf16 v[0:15], v[188:191], v[64:67], v[0:15]
	v_exp_f32_e32 v84, v84
	v_exp_f32_e32 v85, v85
	v_mfma_f32_32x32x16_bf16 v[16:31], v[184:187], v[68:71], v[16:31]
	v_exp_f32_e32 v86, v86
	v_exp_f32_e32 v87, v87
	v_mfma_f32_32x32x16_bf16 v[0:15], v[180:183], v[68:71], v[0:15]
	ds_read_b64_tr_b16 v[192:193], v229 offset:31232
	ds_read_b64_tr_b16 v[194:195], v229 offset:32384
	ds_read_b64_tr_b16 v[188:189], v229 offset:31296
	ds_read_b64_tr_b16 v[190:191], v229 offset:32448
	ds_read_b64_tr_b16 v[184:185], v229 offset:33536
	ds_read_b64_tr_b16 v[186:187], v229 offset:34688
	ds_read_b64_tr_b16 v[180:181], v229 offset:33600
	ds_read_b64_tr_b16 v[182:183], v229 offset:34752
	v_add_f32_e32 v198, v80, v84
	v_add_f32_e32 v199, v81, v85
	v_mfma_f32_32x32x16_bf16 v[64:79], v[230:233], v[246:249], 0
	v_add_f32_e32 v204, v82, v86
	v_add_f32_e32 v205, v83, v87
	v_exp_f32_e32 v88, v88
	v_mfma_f32_32x32x16_bf16 v[64:79], v[176:179], v[120:123], v[64:79]
	v_exp_f32_e32 v89, v89
	v_exp_f32_e32 v90, v90
	v_exp_f32_e32 v91, v91
	v_mfma_f32_32x32x16_bf16 v[64:79], v[172:175], v[124:127], v[64:79]
	v_add_f32_e32 v198, v198, v88
	v_add_f32_e32 v199, v199, v89
	v_add_f32_e32 v204, v204, v90
	v_mfma_f32_32x32x16_bf16 v[64:79], v[168:171], v[128:131], v[64:79]
	v_add_f32_e32 v205, v205, v91
	v_exp_f32_e32 v92, v92
	v_exp_f32_e32 v93, v93
	v_mfma_f32_32x32x16_bf16 v[64:79], v[164:167], v[132:135], v[64:79]
	v_exp_f32_e32 v94, v94
	v_exp_f32_e32 v95, v95
	v_add_f32_e32 v198, v198, v92
	v_mfma_f32_32x32x16_bf16 v[64:79], v[160:163], v[140:143], v[64:79]
	v_add_f32_e32 v199, v199, v93
	v_add_f32_e32 v204, v204, v94
	v_add_f32_e32 v205, v205, v95
	v_mfma_f32_32x32x16_bf16 v[64:79], v[156:159], v[136:139], v[64:79]
	v_add_f32_e32 v198, v198, v199
	v_add_f32_e32 v204, v204, v205
	v_add_f32_e32 v198, v198, v204
	v_cmp_lt_f32_e32 vcc, 0x44800000, v198
	s_or_b32 s8, vcc_lo, vcc_hi
	s_mov_b32 s9, s8
	s_cbranch_scc1 .Lp7_rare_10
.Lp7_back_10:
	v_cvt_pk_bf16_f32 v80, v80, v81
	v_cvt_pk_bf16_f32 v81, v82, v83
	v_cvt_pk_bf16_f32 v82, v84, v85
	v_cvt_pk_bf16_f32 v83, v86, v87
	v_add_f32_e32 v212, v212, v198
	v_cvt_pk_bf16_f32 v84, v88, v89
	v_cvt_pk_bf16_f32 v85, v90, v91
	v_cvt_pk_bf16_f32 v86, v92, v93
	v_cvt_pk_bf16_f32 v87, v94, v95
	v_exp_f32_e32 v64, v64
	v_exp_f32_e32 v65, v65
	v_exp_f32_e32 v66, v66
	v_exp_f32_e32 v67, v67
	v_exp_f32_e32 v68, v68
	v_exp_f32_e32 v69, v69
	v_exp_f32_e32 v70, v70
	v_exp_f32_e32 v71, v71
	s_waitcnt lgkmcnt(6)
	v_mfma_f32_32x32x16_bf16 v[48:63], v[192:195], v[80:83], v[48:63]
	v_add_f32_e32 v198, v64, v68
	v_add_f32_e32 v199, v65, v69
	v_add_f32_e32 v204, v66, v70
	v_add_f32_e32 v205, v67, v71
	v_exp_f32_e32 v72, v72
	v_exp_f32_e32 v73, v73
	v_exp_f32_e32 v74, v74
	v_exp_f32_e32 v75, v75
	s_waitcnt lgkmcnt(4)
	v_mfma_f32_32x32x16_bf16 v[32:47], v[188:191], v[80:83], v[32:47]
	v_add_f32_e32 v198, v198, v72
	v_add_f32_e32 v199, v199, v73
	v_add_f32_e32 v204, v204, v74
	v_add_f32_e32 v205, v205, v75
	v_exp_f32_e32 v76, v76
	v_exp_f32_e32 v77, v77
	v_exp_f32_e32 v78, v78
	v_exp_f32_e32 v79, v79
	s_waitcnt lgkmcnt(2)
	v_mfma_f32_32x32x16_bf16 v[48:63], v[184:187], v[84:87], v[48:63]
	v_add_f32_e32 v198, v198, v76
	v_add_f32_e32 v199, v199, v77
	v_add_f32_e32 v204, v204, v78
	v_add_f32_e32 v205, v205, v79
	v_add_f32_e32 v198, v198, v199
	v_add_f32_e32 v204, v204, v205
	v_add_f32_e32 v198, v198, v204
	v_cmp_lt_f32_e32 vcc, 0x44800000, v198
	s_waitcnt lgkmcnt(0)
	v_mfma_f32_32x32x16_bf16 v[32:47], v[180:183], v[84:87], v[32:47]
	s_or_b32 s8, vcc_lo, vcc_hi
	s_mov_b32 s9, s8
	s_cbranch_scc1 .Lp7_rare_11

; template <int DQ, bool BIAS, bool TAIL>
; __device__ __forceinline__ void attn_item(const AttnItem& A, LAS unsigned char* lds, int wave_s_) {
;     ...
;                 const bool need0 = first || mx[0] > RESCALE_THR, need1 = first || mx[1] > RESCALE_THR;
;                 if (__builtin_amdgcn_ballot_w64(need0 || need1) != 0ull) {
; #pragma unroll
;                     for (int qb = 0; qb < 2; ++qb) {
;                         const float delta = (qb == 0 ? need0 : need1) ? mx[qb] : 0.f, alpha = __builtin_amdgcn_exp2f(-delta);
; #pragma unroll
;                         for (int i = 0; i < 16; ++i) { o[0][qb][i] *= alpha; o[1][qb][i] *= alpha; }
;                         lrun[qb] *= alpha; mref[qb] += delta;
;                     }
;                     first = false;
;                 }
.Lp7_rare_00:
	s_nop 15
	v_max3_f32 v199, v80, v81, v82
	v_max3_f32 v204, v83, v84, v85
	v_max3_f32 v205, v86, v87, v88
	v_max3_f32 v234, v89, v90, v91
	v_max3_f32 v235, v92, v93, v94
	v_max3_f32 v199, v199, v204, v205
	v_max3_f32 v234, v234, v235, v95
	v_max_f32_e32 v199, v199, v234
	v_mov_b32_e32 v204, v199
	s_nop 1
	v_permlane32_swap_b32_e32 v204, v199
	s_nop 1
	v_max_f32_e32 v199, v204, v199
	v_frexp_exp_i32_f32_e32 v204, v199
	v_cndmask_b32_e64 v204, 0, v204, s[8:9]
	v_cvt_f32_i32_e32 v205, v204
	v_add_f32_e32 v205, v211, v205
	v_xor_b32_e32 v234, 0x80000000, v205
	v_cvt_pk_bf16_f32 v234, v234, 0
	v_lshlrev_b32_e32 v235, 16, v234
	v_add_f32_e32 v205, v211, v235
	v_exp_f32_e32 v205, v205
	v_xor_b32_e32 v211, 0x80000000, v235
	v_mov_b32_e32 v238, 0
	s_mov_b32 exec_hi, 0
	v_mov_b32_e32 v238, v234
	s_mov_b32 exec_hi, -1
	v_mul_f32_e32 v80, v80, v205
	v_mul_f32_e32 v81, v81, v205
	v_mul_f32_e32 v82, v82, v205
	v_mul_f32_e32 v83, v83, v205
	v_mul_f32_e32 v84, v84, v205
	v_mul_f32_e32 v85, v85, v205
	v_mul_f32_e32 v86, v86, v205
	v_mul_f32_e32 v87, v87, v205
	v_mul_f32_e32 v88, v88, v205
	v_mul_f32_e32 v89, v89, v205
	v_mul_f32_e32 v90, v90, v205
	v_mul_f32_e32 v91, v91, v205
	v_mul_f32_e32 v92, v92, v205
	v_mul_f32_e32 v93, v93, v205
	v_mul_f32_e32 v94, v94, v205
	v_mul_f32_e32 v95, v95, v205
	v_mul_f32_e32 v198, v198, v205
	v_mul_f32_e32 v212, v212, v205
	v_mul_f32_e32 v32, v32, v205
	v_mul_f32_e32 v33, v33, v205
	v_mul_f32_e32 v34, v34, v205
	v_mul_f32_e32 v35, v35, v205
	v_mul_f32_e32 v36, v36, v205
	v_mul_f32_e32 v37, v37, v205
	v_mul_f32_e32 v38, v38, v205
	v_mul_f32_e32 v39, v39, v205
	v_mul_f32_e32 v40, v40, v205
	v_mul_f32_e32 v41, v41, v205
	v_mul_f32_e32 v42, v42, v205
	v_mul_f32_e32 v43, v43, v205
	v_mul_f32_e32 v44, v44, v205
	v_mul_f32_e32 v45, v45, v205
	v_mul_f32_e32 v46, v46, v205
	v_mul_f32_e32 v47, v47, v205
	v_mul_f32_e32 v48, v48, v205
	v_mul_f32_e32 v49, v49, v205
	v_mul_f32_e32 v50, v50, v205
	v_mul_f32_e32 v51, v51, v205
	v_mul_f32_e32 v52, v52, v205
	v_mul_f32_e32 v53, v53, v205
	v_mul_f32_e32 v54, v54, v205
	v_mul_f32_e32 v55, v55, v205
	v_mul_f32_e32 v56, v56, v205
	v_mul_f32_e32 v57, v57, v205
	v_mul_f32_e32 v58, v58, v205
	v_mul_f32_e32 v59, v59, v205
	v_mul_f32_e32 v60, v60, v205
	v_mul_f32_e32 v61, v61, v205
	v_mul_f32_e32 v62, v62, v205
	v_mul_f32_e32 v63, v63, v205
	s_branch .Lp7_back_00
.Lp7_rare_01:
	s_nop 15
	v_max3_f32 v199, v64, v65, v66
	v_max3_f32 v204, v67, v68, v69
	v_max3_f32 v205, v70, v71, v72
	v_max3_f32 v234, v73, v74, v75
	v_max3_f32 v235, v76, v77, v78
	v_max3_f32 v199, v199, v204, v205
	v_max3_f32 v234, v234, v235, v79
	v_max_f32_e32 v199, v199, v234
	v_mov_b32_e32 v204, v199
	s_nop 1
	v_permlane32_swap_b32_e32 v204, v199
	s_nop 1
	v_max_f32_e32 v199, v204, v199
	v_frexp_exp_i32_f32_e32 v204, v199
	v_cndmask_b32_e64 v204, 0, v204, s[8:9]
	v_cvt_f32_i32_e32 v205, v204
	v_add_f32_e32 v205, v223, v205
	v_xor_b32_e32 v234, 0x80000000, v205
	v_cvt_pk_bf16_f32 v234, v234, 0
	v_lshlrev_b32_e32 v235, 16, v234
	v_add_f32_e32 v205, v223, v235
	v_exp_f32_e32 v205, v205
	v_xor_b32_e32 v223, 0x80000000, v235
	v_mov_b32_e32 v246, 0
	s_mov_b32 exec_hi, 0
	v_mov_b32_e32 v246, v234
	s_mov_b32 exec_hi, -1
	v_mul_f32_e32 v64, v64, v205
	v_mul_f32_e32 v65, v65, v205
	v_mul_f32_e32 v66, v66, v205
	v_mul_f32_e32 v67, v67, v205
	v_mul_f32_e32 v68, v68, v205
	v_mul_f32_e32 v69, v69, v205
	v_mul_f32_e32 v70, v70, v205
	v_mul_f32_e32 v71, v71, v205
	v_mul_f32_e32 v72, v72, v205
	v_mul_f32_e32 v73, v73, v205
	v_mul_f32_e32 v74, v74, v205
	v_mul_f32_e32 v75, v75, v205
	v_mul_f32_e32 v76, v76, v205
	v_mul_f32_e32 v77, v77, v205
	v_mul_f32_e32 v78, v78, v205
	v_mul_f32_e32 v79, v79, v205
	v_mul_f32_e32 v198, v198, v205
	v_mul_f32_e32 v213, v213, v205
	v_mul_f32_e32 v0, v0, v205
	v_mul_f32_e32 v1, v1, v205
	v_mul_f32_e32 v2, v2, v205
	v_mul_f32_e32 v3, v3, v205
	v_mul_f32_e32 v4, v4, v205
	v_mul_f32_e32 v5, v5, v205
	v_mul_f32_e32 v6, v6, v205
	v_mul_f32_e32 v7, v7, v205
	v_mul_f32_e32 v8, v8, v205
	v_mul_f32_e32 v9, v9, v205
	v_mul_f32_e32 v10, v10, v205
	v_mul_f32_e32 v11, v11, v205
	v_mul_f32_e32 v12, v12, v205
	v_mul_f32_e32 v13, v13, v205
	v_mul_f32_e32 v14, v14, v205
	v_mul_f32_e32 v15, v15, v205
	v_mul_f32_e32 v16, v16, v205
	v_mul_f32_e32 v17, v17, v205
	v_mul_f32_e32 v18, v18, v205
	v_mul_f32_e32 v19, v19, v205
	v_mul_f32_e32 v20, v20, v205
	v_mul_f32_e32 v21, v21, v205
	v_mul_f32_e32 v22, v22, v205
	v_mul_f32_e32 v23, v23, v205
	v_mul_f32_e32 v24, v24, v205
	v_mul_f32_e32 v25, v25, v205
	v_mul_f32_e32 v26, v26, v205
	v_mul_f32_e32 v27, v27, v205
	v_mul_f32_e32 v28, v28, v205
	v_mul_f32_e32 v29, v29, v205
	v_mul_f32_e32 v30, v30, v205
	v_mul_f32_e32 v31, v31, v205
	s_branch .Lp7_back_01

; template <int DQ, bool BIAS, bool TAIL>
; __device__ __forceinline__ void attn_item(const AttnItem& A, LAS unsigned char* lds, int wave_s_) {
;     ...
;                 const bool need0 = first || mx[0] > RESCALE_THR, need1 = first || mx[1] > RESCALE_THR;
;                 if (__builtin_amdgcn_ballot_w64(need0 || need1) != 0ull) {
; #pragma unroll
;                     for (int qb = 0; qb < 2; ++qb) {
;                         const float delta = (qb == 0 ? need0 : need1) ? mx[qb] : 0.f, alpha = __builtin_amdgcn_exp2f(-delta);
; #pragma unroll
;                         for (int i = 0; i < 16; ++i) { o[0][qb][i] *= alpha; o[1][qb][i] *= alpha; }
;                         lrun[qb] *= alpha; mref[qb] += delta;
;                     }
;                     first = false;
;                 }
.Lp7_fix:
	s_nop 15
	s_nop 7
	v_mov_b32_e32 v198, 0x3f80
	v_mov_b32_e32 v230, 0
	s_mov_b32 exec_hi, 0
	v_mov_b32_e32 v230, v198
	s_mov_b32 exec_hi, -1
	v_mov_b32_e32 v231, 0
	v_mov_b32_e32 v232, 0
	v_mov_b32_e32 v233, 0
	v_xor_b32_e32 v234, 0x80000000, v211
	v_cvt_pk_bf16_f32 v234, v234, 0
	v_lshlrev_b32_e32 v235, 16, v234
	v_add_f32_e32 v205, v211, v235
	v_exp_f32_e32 v205, v205
	v_xor_b32_e32 v211, 0x80000000, v235
	v_mov_b32_e32 v238, 0
	s_mov_b32 exec_hi, 0
	v_mov_b32_e32 v238, v234
	s_mov_b32 exec_hi, -1
	v_mov_b32_e32 v239, 0
	v_mov_b32_e32 v240, 0
	v_mov_b32_e32 v241, 0
	v_mul_f32_e32 v212, v212, v205
	v_mul_f32_e32 v32, v32, v205
	v_mul_f32_e32 v33, v33, v205
	v_mul_f32_e32 v34, v34, v205
	v_mul_f32_e32 v35, v35, v205
	v_mul_f32_e32 v36, v36, v205
	v_mul_f32_e32 v37, v37, v205
	v_mul_f32_e32 v38, v38, v205
	v_mul_f32_e32 v39, v39, v205
	v_mul_f32_e32 v40, v40, v205
	v_mul_f32_e32 v41, v41, v205
	v_mul_f32_e32 v42, v42, v205
	v_mul_f32_e32 v43, v43, v205
	v_mul_f32_e32 v44, v44, v205
	v_mul_f32_e32 v45, v45, v205
	v_mul_f32_e32 v46, v46, v205
	v_mul_f32_e32 v47, v47, v205
	v_mul_f32_e32 v48, v48, v205
	v_mul_f32_e32 v49, v49, v205
	v_mul_f32_e32 v50, v50, v205
	v_mul_f32_e32 v51, v51, v205
	v_mul_f32_e32 v52, v52, v205
	v_mul_f32_e32 v53, v53, v205
	v_mul_f32_e32 v54, v54, v205
	v_mul_f32_e32 v55, v55, v205
	v_mul_f32_e32 v56, v56, v205
	v_mul_f32_e32 v57, v57, v205
	v_mul_f32_e32 v58, v58, v205
	v_mul_f32_e32 v59, v59, v205
	v_mul_f32_e32 v60, v60, v205
	v_mul_f32_e32 v61, v61, v205
	v_mul_f32_e32 v62, v62, v205
	v_mul_f32_e32 v63, v63, v205
	v_xor_b32_e32 v234, 0x80000000, v223
	v_cvt_pk_bf16_f32 v234, v234, 0
	v_lshlrev_b32_e32 v235, 16, v234
	v_add_f32_e32 v205, v223, v235
	v_exp_f32_e32 v205, v205
	v_xor_b32_e32 v223, 0x80000000, v235
	v_mov_b32_e32 v246, 0
	s_mov_b32 exec_hi, 0
	v_mov_b32_e32 v246, v234
	s_mov_b32 exec_hi, -1
	v_mov_b32_e32 v247, 0
	v_mov_b32_e32 v248, 0
	v_mov_b32_e32 v249, 0
	v_mul_f32_e32 v213, v213, v205
	v_mul_f32_e32 v0, v0, v205
	v_mul_f32_e32 v1, v1, v205
	v_mul_f32_e32 v2, v2, v205
	v_mul_f32_e32 v3, v3, v205
	v_mul_f32_e32 v4, v4, v205
	v_mul_f32_e32 v5, v5, v205
	v_mul_f32_e32 v6, v6, v205
	v_mul_f32_e32 v7, v7, v205
	v_mul_f32_e32 v8, v8, v205
	v_mul_f32_e32 v9, v9, v205
	v_mul_f32_e32 v10, v10, v205
	v_mul_f32_e32 v11, v11, v205
	v_mul_f32_e32 v12, v12, v205
	v_mul_f32_e32 v13, v13, v205
	v_mul_f32_e32 v14, v14, v205
	v_mul_f32_e32 v15, v15, v205
	v_mul_f32_e32 v16, v16, v205
	v_mul_f32_e32 v17, v17, v205
	v_mul_f32_e32 v18, v18, v205
	v_mul_f32_e32 v19, v19, v205
	v_mul_f32_e32 v20, v20, v205
	v_mul_f32_e32 v21, v21, v205
	v_mul_f32_e32 v22, v22, v205
	v_mul_f32_e32 v23, v23, v205
	v_mul_f32_e32 v24, v24, v205
	v_mul_f32_e32 v25, v25, v205
	v_mul_f32_e32 v26, v26, v205
	v_mul_f32_e32 v27, v27, v205
	v_mul_f32_e32 v28, v28, v205
	v_mul_f32_e32 v29, v29, v205
	v_mul_f32_e32 v30, v30, v205
	v_mul_f32_e32 v31, v31, v205
	s_branch .LBB0_1484
